# grid barrier: member blocks invalidate only L1 (buffer_inv sc0); the XCD's last arriver already invalidated the shared L2 (sc1) before releasing them
# speedup vs baseline: 1.0263x; 1.0263x over previous
; __device__ __forceinline__ unsigned xb_ld(unsigned* p) { return __hip_atomic_load(p, __ATOMIC_RELAXED, __HIP_MEMORY_SCOPE_AGENT); }
; #define XB_SPIN(cond, bar) do { unsigned _sp = 0; while (cond) { __builtin_amdgcn_s_sleep(1); \
;     if ((++_sp & 255u) == 0u) { if (xb_ld(&(bar)[XB_TMO])) break; if (_sp > XB_SPIN_CAP) { atomicAdd(&(bar)[XB_TMO], 1u); break; } } } } while (0)
; __device__ __forceinline__ void xcd_barrier(const XcdBarrier& b) {
;     ...
;     } else {
;       XB_SPIN(xb_ld(&bar[XB_XGEN(b.x)]) == gen, bar);
;       __builtin_amdgcn_fence(__ATOMIC_ACQUIRE, "agent");
;       asm volatile("s_waitcnt vmcnt(0)" ::: "memory");
.LBB0_1358:
	s_or_b64 exec, exec, s[4:5]
	s_waitcnt vmcnt(0)
	buffer_inv sc0
	s_waitcnt vmcnt(0)
